# G1 start skew 0.5us per group instead of 1us (v75 otherwise)
# baseline (speedup 1.0000x reference)
.Lskew_loop_g1:
	s_sleep 16
	s_sub_u32 s4, s4, 1
	s_cmp_lg_u32 s4, 0
	s_cbranch_scc1 .Lskew_loop_g1
